# one static s_setprio 1 for waves 4-7 around the fox attention MFMA loop (reset at loop exit)
# baseline (speedup 1.0000x reference)
; #define LAS __attribute__((address_space(3)))
; __device__ __forceinline__ float swap_add(float m) { auto rr = __builtin_amdgcn_permlane32_swap(__float_as_uint(m), __float_as_uint(m), false, false); return __uint_as_float(rr[0]) + __uint_as_float(rr[1]); }
; #define ATT_WAIT_BAR(pending) do { if (pending) { if (FOX) asm volatile("s_waitcnt vmcnt(5) lgkmcnt(0)\n\ts_barrier" ::: "memory"); else asm volatile("s_waitcnt vmcnt(4) lgkmcnt(0)\n\ts_barrier" ::: "memory"); } \
;         else asm volatile("s_waitcnt vmcnt(0) lgkmcnt(0)\n\ts_barrier" ::: "memory"); } while (0)
; template <bool FOX> ...
;     ...
;     const unsigned krow = (l31 & ~12u) | ((l31 & 4u) << 1) | ((l31 & 8u) >> 1);
;     unsigned koff[4];
; #pragma unroll
;     for (int s = 0; s < 4; ++s) koff[s] = offb(krow, 8 * stream + 2 * s + hi);
;     unsigned voff[NCB][2];
; #pragma unroll
;     for (int cb = 0; cb < NCB; ++cb)
; #pragma unroll
;         for (int t = 0; t < 2; ++t) voff[cb][t] = 16384u + tr_addr(lane, FOX ? 2 * stream + cb : cb, 0, t);
;     f32x16 o[NCB];
; #pragma unroll
;     for (int cb = 0; cb < NCB; ++cb)
; #pragma unroll
;         for (int r = 0; r < 16; ++r) o[cb][r] = 0.f;
;     float lsum = 0.f;
;     const int qloc64 = 32 * (wq & 1) + l31;
;     constexpr float THR = 96.0f, SKIP_T = 40.0f;
;     float ub = 0.f, qb;
;     {
;         float q1 = 0.f;
; #pragma unroll
;         for (int s = 0; s < 4; ++s)
; #pragma unroll
;             for (int e = 0; e < 8; ++e) q1 += fabsf(bf2f((unsigned short)qf[s][e]));
;         q1 = swap_add(q1);
;         qb = q1 * kinf * 1.01f;
;         if (FOX) ub = qb + cq2 + SKIP_T;
;     }
;     bool needmax = true;
;     volatile LAS int* flags = (volatile LAS int*)(lds + ATT_UNITW + 64);
;     int t = FOX ? NT : 1;
;     ATT_DMA(t, 0);
;     { const int t1_ = FOX ? t - 1 : t + 1; const bool h1_ = FOX ? (t1_ >= 1) : (t1_ <= NT); if (h1_) ATT_DMA(t1_, 1); ATT_WAIT_BAR(h1_); }
;     bool wmore = (tq >= 1), first = true;
;     float mref = 0.f;
;     f32x16 negm;
; #pragma unroll
;     for (int r = 0; r < 16; ++r) negm[r] = 0.f;
;     ...
;         if (FOX && t == tq) {
; #pragma unroll
;             for (int r = 0; r < 16; ++r) { const int kl = 16 * (r >> 3) + 8 * hi + (r & 7); if (kl > qloc64) s0[r] = -INFINITY; if (kl + 32 > qloc64) s1[r] = -INFINITY; }
.LBB0_499:
	s_cmp_eq_u32 s5, 1
	s_cselect_b64 vcc, -1, 0
	s_cmp_eq_u32 s5, 2
	v_cndmask_b32_e32 v7, v227, v228, vcc
	s_cselect_b64 vcc, -1, 0
	s_cmp_eq_u32 s5, 3
	v_cndmask_b32_e32 v7, v7, v229, vcc
	s_cselect_b64 vcc, -1, 0
	s_cmp_eq_u32 s5, 4
	v_cndmask_b32_e32 v7, v7, v230, vcc
	s_cselect_b64 vcc, -1, 0
	s_cmp_eq_u32 s5, 5
	v_cndmask_b32_e32 v7, v7, v231, vcc
	s_cselect_b64 vcc, -1, 0
	s_cmp_eq_u32 s5, 6
	v_cndmask_b32_e32 v7, v7, v232, vcc
	s_cselect_b64 vcc, -1, 0
	s_cmp_eq_u32 s5, 7
	v_cndmask_b32_e32 v7, v7, v233, vcc
	s_cselect_b64 vcc, -1, 0
	s_or_b32 s5, s5, 1
	s_cmp_eq_u32 s5, 1
	v_cndmask_b32_e32 v7, v7, v234, vcc
	s_cselect_b64 vcc, -1, 0
	s_cmp_eq_u32 s5, 2
	v_cndmask_b32_e32 v8, v227, v228, vcc
	s_cselect_b64 vcc, -1, 0
	s_cmp_eq_u32 s5, 3
	v_cndmask_b32_e32 v8, v8, v229, vcc
	s_cselect_b64 vcc, -1, 0
	s_cmp_eq_u32 s5, 4
	v_cndmask_b32_e32 v8, v8, v230, vcc
	s_cselect_b64 vcc, -1, 0
	s_cmp_eq_u32 s5, 5
	v_cndmask_b32_e32 v8, v8, v231, vcc
	s_cselect_b64 vcc, -1, 0
	s_cmp_eq_u32 s5, 6
	v_cndmask_b32_e32 v8, v8, v232, vcc
	s_cselect_b64 vcc, -1, 0
	s_cmp_eq_u32 s5, 7
	v_cndmask_b32_e32 v8, v8, v233, vcc
	s_cselect_b64 vcc, -1, 0
	v_cndmask_b32_e32 v8, v8, v234, vcc
	v_max_f32_e32 v7, v7, v7
	v_max_f32_e32 v8, v8, v8
	v_lshrrev_b32_e32 v9, 1, v3
	v_max_f32_e32 v7, v7, v8
	v_lshlrev_b32_e32 v8, 1, v3
	v_and_b32_e32 v9, 4, v9
	v_and_or_b32 v8, v8, 8, v9
	s_lshr_b32 s10, s1, 1
	v_and_or_b32 v9, v3, 19, v8
	s_or_b32 s1, s10, s3
	s_lshl_b32 s3, s4, 3
	v_lshlrev_b32_e32 v149, 8, v9
	v_lshlrev_b32_e32 v9, 2, v3
	v_or_b32_e32 v10, s3, v17
	v_and_b32_e32 v9, 12, v9
	v_lshrrev_b32_e32 v8, 2, v8
	v_or_b32_e32 v11, v8, v9
	v_bitop3_b32 v8, v8, v10, v9 bitop3:0x36
	v_lshlrev_b32_e32 v150, 4, v8
	v_bitop3_b32 v8, v10, v11, 2 bitop3:0x36
	v_lshlrev_b32_e32 v151, 4, v8
	v_bitop3_b32 v8, v10, v11, 4 bitop3:0x36
	v_lshrrev_b32_e32 v9, 3, v3
	v_lshlrev_b32_e32 v152, 4, v8
	v_bitop3_b32 v8, v10, v11, 6 bitop3:0x36
	v_and_b32_e32 v9, 2, v9
	v_bfe_u32 v10, v3, 1, 1
	v_lshlrev_b32_e32 v148, 3, v17
	v_or3_b32 v9, v9, v10, s3
	s_lshl_b32 s3, s0, 5
	v_lshlrev_b32_e32 v10, 3, v1
	v_and_or_b32 v2, s3, 32, v2
	v_cmp_eq_u32_e64 s[42:43], 0, v1
	v_or_b32_e32 v1, 32, v148
	v_cmp_gt_u32_e64 s[46:47], v1, v2
	v_or_b32_e32 v1, 33, v148
	v_cmp_gt_u32_e64 s[50:51], v1, v2
	v_or_b32_e32 v1, 2, v148
	v_cmp_gt_u32_e64 s[52:53], v1, v2
	v_or_b32_e32 v1, 34, v148
	v_cmp_gt_u32_e64 s[54:55], v1, v2
	v_or_b32_e32 v1, 3, v148
	v_cmp_gt_u32_e64 s[56:57], v1, v2
	v_or_b32_e32 v1, 35, v148
	v_cmp_gt_u32_e64 s[58:59], v1, v2
	v_or_b32_e32 v1, 4, v148
	v_cmp_gt_u32_e64 s[60:61], v1, v2
	v_or_b32_e32 v1, 36, v148
	v_cmp_gt_u32_e64 s[62:63], v1, v2
	v_or_b32_e32 v1, 5, v148
	v_cmp_gt_u32_e64 s[64:65], v1, v2
	v_or_b32_e32 v1, 37, v148
	v_cmp_gt_u32_e64 s[66:67], v1, v2
	v_or_b32_e32 v1, 6, v148
	v_cmp_gt_u32_e64 s[68:69], v1, v2
	v_or_b32_e32 v1, 38, v148
	v_cmp_gt_u32_e64 s[70:71], v1, v2
	v_or_b32_e32 v1, 7, v148
	v_cmp_gt_u32_e64 s[72:73], v1, v2
	v_or_b32_e32 v1, 39, v148
	v_cmp_gt_u32_e64 s[74:75], v1, v2
	v_or_b32_e32 v1, 16, v148
	v_cmp_gt_u32_e64 s[76:77], v1, v2
	v_or_b32_e32 v1, 48, v148
	v_cmp_gt_u32_e64 s[78:79], v1, v2
	v_or_b32_e32 v1, 17, v148
	v_cmp_gt_u32_e64 s[80:81], v1, v2
	v_or_b32_e32 v1, 49, v148
	v_cmp_gt_u32_e64 s[82:83], v1, v2
	v_or_b32_e32 v1, 18, v148
	v_cmp_gt_u32_e64 s[84:85], v1, v2
	v_or_b32_e32 v1, 50, v148
	v_cmp_gt_u32_e64 s[86:87], v1, v2
	v_or_b32_e32 v1, 19, v148
	v_cmp_gt_u32_e64 s[88:89], v1, v2
	v_or_b32_e32 v1, 51, v148
	v_cmp_gt_u32_e64 s[90:91], v1, v2
	v_or_b32_e32 v1, 20, v148
	v_cmp_gt_u32_e64 s[92:93], v1, v2
	v_or_b32_e32 v1, 52, v148
	v_cmp_gt_u32_e64 s[94:95], v1, v2
	v_or_b32_e32 v1, 21, v148
	v_cmp_gt_u32_e64 s[96:97], v1, v2
	v_or_b32_e32 v1, 53, v148
	v_lshlrev_b32_e32 v153, 4, v8
	v_lshrrev_b32_e32 v8, 2, v3
	s_cmp_lg_u32 s1, 0
	v_cmp_gt_u32_e64 s[98:99], v1, v2
	v_or_b32_e32 v1, 22, v148
	v_and_b32_e32 v8, 11, v8
	v_add_f32_e32 v5, v5, v6
	s_cselect_b64 s[20:21], -1, 0
	v_writelane_b32 v250, s14, 8
	s_lshl_b32 s4, s14, 2
	v_cmp_gt_u32_e64 s[38:39], v1, v2
	v_or_b32_e32 v1, 54, v148
	v_and_b32_e32 v3, 12, v3
	v_lshrrev_b32_e32 v11, 2, v8
	v_or_b32_e32 v13, 4, v8
	v_mul_f32_e32 v5, v7, v5
	s_add_i32 s22, s4, 0
	v_cmp_gt_u32_e64 s[4:5], v1, v2
	v_or_b32_e32 v1, 23, v148
	v_and_b32_e32 v10, 8, v10
	v_or_b32_e32 v12, v11, v3
	v_lshrrev_b32_e32 v14, 2, v13
	v_or_b32_e32 v18, 4, v9
	v_mul_f32_e32 v155, 0x3f8147ae, v5
	s_lshl_b32 s0, s0, 2
	v_cmp_gt_u32_e64 s[6:7], v1, v2
	v_or_b32_e32 v1, 55, v148
	v_bitop3_b32 v11, v11, v9, v3 bitop3:0x36
	v_bitop3_b32 v15, v14, v9, v3 bitop3:0x36
	v_bitop3_b32 v9, v9, v12, 4 bitop3:0x36
	v_bitop3_b32 v3, v14, v18, v3 bitop3:0x36
	v_mul_f32_e32 v154, 0x3fb8aa3b, v4
	v_fmamk_f32 v4, v4, 0x3fb8aa3b, v155
	s_add_i32 s23, s0, 0
	v_cmp_gt_u32_e64 s[44:45], v148, v2
	v_cmp_lt_u32_e64 s[48:49], v148, v2
	v_cmp_gt_u32_e64 s[8:9], v1, v2
	v_lshl_or_b32 v1, v8, 8, v10
	v_lshl_or_b32 v2, v13, 8, v10
	s_add_i32 s12, s10, -1
	s_lshl_b32 s0, s2, 1
	s_lshl_b32 s2, s2, 7
	v_mov_b32_e32 v98, 0
	v_mov_b32_e32 v161, 0
	v_add_f32_e32 v156, 0x42200000, v4
	s_mov_b32 s3, 0
	s_add_i32 s22, s22, 0x20000
	s_add_i32 s23, s23, 0x20840
	v_lshl_add_u32 v159, v11, 4, v1
	v_lshl_add_u32 v160, v15, 4, v2
	v_lshl_add_u32 v158, v9, 4, v1
	v_lshl_add_u32 v157, v3, 4, v2
	s_sub_i32 s0, 0x82, s0
	s_sub_i32 s16, 0x1fc0, s2
	s_mov_b64 s[10:11], -1
	v_mov_b32_e32 v162, s12
	v_mov_b32_e32 v110, 0
	v_mov_b32_e32 v111, 0
	v_mov_b32_e32 v112, 0
	v_mov_b32_e32 v113, 0
	s_mov_b32 s33, 0
	s_mov_b64 s[24:25], -1
	v_mov_b32_e32 v135, 0
	v_mov_b32_e32 v99, v98
	v_mov_b32_e32 v100, v98
	v_mov_b32_e32 v101, v98
	v_mov_b32_e32 v102, v98
	v_mov_b32_e32 v103, v98
	v_mov_b32_e32 v104, v98
	v_mov_b32_e32 v105, v98
	v_mov_b32_e32 v106, v98
	v_mov_b32_e32 v107, v98
	v_mov_b32_e32 v108, v98
	v_mov_b32_e32 v109, v98
	v_mov_b32_e32 v34, 0
	v_mov_b32_e32 v35, v161
	v_mov_b32_e32 v36, v161
	v_mov_b32_e32 v37, v161
	v_mov_b32_e32 v38, v161
	v_mov_b32_e32 v39, v161
	v_mov_b32_e32 v40, v161
	v_mov_b32_e32 v41, v161
	v_mov_b32_e32 v42, v161
	v_mov_b32_e32 v43, v161
	v_mov_b32_e32 v44, v161
	v_mov_b32_e32 v45, v161
	v_mov_b32_e32 v46, v161
	v_mov_b32_e32 v47, v161
	v_mov_b32_e32 v48, v161
	v_mov_b32_e32 v49, v161
	v_mov_b32_e32 v18, 0
	v_mov_b32_e32 v19, v161
	v_mov_b32_e32 v20, v161
	v_mov_b32_e32 v21, v161
	v_mov_b32_e32 v22, v161
	v_mov_b32_e32 v23, v161
	v_mov_b32_e32 v24, v161
	v_mov_b32_e32 v25, v161
	v_mov_b32_e32 v26, v161
	v_mov_b32_e32 v27, v161
	v_mov_b32_e32 v28, v161
	v_mov_b32_e32 v29, v161
	v_mov_b32_e32 v30, v161
	v_mov_b32_e32 v31, v161
	v_mov_b32_e32 v32, v161
	v_mov_b32_e32 v33, v161
	v_writelane_b32 v250, s15, 9
	v_readfirstlane_b32 s34, v210
	s_cmp_lt_u32 s34, 0x100
	s_cbranch_scc1 .Lfox_noprio
	s_setprio 1
; #define LAS __attribute__((address_space(3)))
; template <bool FOX> ...
;     ...
;         const int tn = FOX ? t - 1 : t + 1, tn2 = FOX ? t - 2 : t + 2;
;         const bool have_next = FOX ? (tn >= 1) : (tn <= NT), have_next2 = FOX ? (tn2 >= 1) : (tn2 <= NT);
;         const int nbuf = (buf + 1) & 3;
;         const bool act = (t <= tq) && wmore;
;         LAS const unsigned char* vbp_ = lds + pbuf * 32768;
;         LAS const unsigned char* kb = lds + buf * 32768;
;         s16x4 va[NCB][2];
;         f32x16 s0, s1;
;         float ckfirst = 0.f, alpha_o = 1.f; bool resc = false;
;         if (act) {
;             bf16x8 kf[8];
; #pragma unroll
;             for (int s = 0; s < 4; ++s) { kf[2 * s] = *(LAS const bf16x8*)(kb + koff[s]); kf[2 * s + 1] = *(LAS const bf16x8*)(kb + koff[s] + 8192); }
;             if (have_next2) ATT_DMA(tn2, (buf + 2) & 3);
.Lfox_noprio:
.LBB0_500:
	s_add_i32 s34, s0, -1
	s_cmp_gt_i32 s34, 2
	s_mov_b32 s18, s3
	s_cselect_b64 s[2:3], -1, 0
	s_cmp_lt_i32 s34, 3
	s_cselect_b64 s[28:29], -1, 0
	s_cmp_le_i32 s34, s1
	s_cselect_b64 s[12:13], -1, 0
	s_and_b64 s[40:41], s[12:13], s[20:21]
	v_cndmask_b32_e64 v1, 0, 1, s[40:41]
	v_cmp_ne_u32_e64 s[12:13], 1, v1
	v_cndmask_b32_e64 v1, 0, 1, s[2:3]
	s_andn2_b64 vcc, exec, s[40:41]
	v_cmp_ne_u32_e64 s[14:15], 1, v1
	s_mov_b64 s[2:3], -1
	s_cbranch_vccz .LBB0_504
	s_and_b64 vcc, exec, s[14:15]
	s_cbranch_vccnz .LBB0_503
	s_xor_b32 s19, s18, 2
	s_lshl_b32 s2, s19, 15
	s_add_i32 vcc_lo, s30, s2
	s_lshl_b64 s[2:3], s[16:17], 10
	v_lshl_add_u64 v[2:3], v[140:141], 0, s[2:3]
	s_mov_b32 m0, vcc_lo
	s_nop 0
	global_load_lds_dwordx4 v[2:3], off
	v_lshl_add_u64 v[2:3], v[144:145], 0, s[2:3]
	s_add_i32 m0, vcc_lo, 0x400
	s_nop 0
	global_load_lds_dwordx4 v[2:3], off
	v_lshl_add_u64 v[2:3], v[138:139], 0, s[2:3]
	s_add_i32 m0, vcc_lo, 0x4000
	s_nop 0
	global_load_lds_dwordx4 v[2:3], off
	v_lshl_add_u64 v[2:3], v[142:143], 0, s[2:3]
	s_add_i32 m0, vcc_lo, 0x4400
	s_lshl_b64 s[2:3], s[16:17], 5
	global_load_lds_dwordx4 v[2:3], off
	v_lshl_add_u64 v[2:3], v[146:147], 0, s[2:3]
	s_lshl_b32 s2, s19, 9
	s_add_i32 m0, s31, s2
	s_nop 0
	global_load_lds_dword v[2:3], off

; #define LAS __attribute__((address_space(3)))
; __device__ __forceinline__ float swap_add(float m) { auto rr = __builtin_amdgcn_permlane32_swap(__float_as_uint(m), __float_as_uint(m), false, false); return __uint_as_float(rr[0]) + __uint_as_float(rr[1]); }
; #define ATT_SB() __builtin_amdgcn_sched_barrier(0)
; #define ATT_VRD(arr, ks) do { _Pragma("unroll") for (int cb = 0; cb < NCB; ++cb) { arr[cb][0] = vtr(vbp_ + voff[cb][0] + 4096 * (ks)); arr[cb][1] = vtr(vbp_ + voff[cb][1] + 4096 * (ks)); } } while (0)
; #define ATT_MM(arr, ks) do { _Pragma("unroll") for (int cb = 0; cb < NCB; ++cb) { const bf16x8 vf = {arr[cb][0][0], arr[cb][0][1], arr[cb][0][2], arr[cb][0][3], arr[cb][1][0], arr[cb][1][1], arr[cb][1][2], arr[cb][1][3]}; o[cb] = MFMA32(vf, pf[ks], o[cb]); } } while (0)
; template <bool FOX> ...
;     ...
;     u32x2 gpre[NCB][4];
; #pragma unroll
;     for (int cb = 0; cb < NCB; ++cb)
; #pragma unroll
;         for (int gq = 0; gq < 4; ++gq) gpre[cb][gq] = (u32x2){0u, 0u};
;     if (FOX || stream == 0) {
;         const bf16_t* gp_ = G + (rowb + qrow) * 512 + 128 * g + (FOX ? 64 * stream : 0) + 4 * hi;
; #pragma unroll
;         for (int cb = 0; cb < NCB; ++cb)
; #pragma unroll
;             for (int gq = 0; gq < 4; ++gq) gpre[cb][gq] = *(const u32x2*)(gp_ + 32 * cb + 8 * gq);
;     }
;     { LAS const unsigned char* vbp_ = lds + pbuf * 32768; s16x4 va[NCB][2];
;         ATT_VRD(va, 0); ATT_SB();
;         ATT_MM(va, 0); ATT_VRD(va, 1); ATT_SB();
;         ATT_MM(va, 1); ATT_VRD(va, 2); ATT_SB();
;         ATT_MM(va, 2); ATT_VRD(va, 3); ATT_SB();
;         ATT_MM(va, 3); ATT_SB(); }
;     ...
;     if (!FOX) __syncthreads();
;     lsum = swap_add(lsum);
;     const float invl = 1.0f / lsum;
;     int qrow_e = qrow; asm volatile("" : "+v"(qrow_e));
;     const int grow_i = g_row(b, qrow_e);
;     const size_t grow = (size_t)(grow_i < 0 ? MROWS - 1 : grow_i);
.LBB0_533:
	s_setprio 0
	v_readlane_b32 s0, v253, 18
	v_lshlrev_b64 v[2:3], 10, v[136:137]
	v_readlane_b32 s1, v253, 19
	v_readlane_b32 s7, v250, 7
	s_lshl_b32 s16, s7, 1
	v_lshl_add_u64 v[2:3], s[0:1], 0, v[2:3]
	v_readlane_b32 s8, v250, 8
	v_lshl_add_u64 v[2:3], v[2:3], 0, s[16:17]
	v_readlane_b32 s9, v250, 9
	v_mov_b32_e32 v149, v0
	v_add_u32_e32 v1, s2, v159
	v_lshl_add_u64 v[2:3], s[8:9], 1, v[2:3]
	v_lshl_add_u64 v[2:3], v[2:3], 0, v[148:149]
	global_load_dwordx2 v[50:51], v[2:3], off
	global_load_dwordx2 v[14:15], v[2:3], off offset:16
	global_load_dwordx2 v[12:13], v[2:3], off offset:32
	global_load_dwordx2 v[10:11], v[2:3], off offset:48
	global_load_dwordx2 v[8:9], v[2:3], off offset:64
	global_load_dwordx2 v[6:7], v[2:3], off offset:80
	global_load_dwordx2 v[4:5], v[2:3], off offset:96
	s_nop 0
	global_load_dwordx2 v[2:3], v[2:3], off offset:112
	v_add_u32_e32 v60, s2, v160
	v_add_u32_e32 v61, s2, v158
	v_add_u32_e32 v62, s2, v157
	ds_read_b64_tr_b16 v[52:53], v1 offset:16384
	ds_read_b64_tr_b16 v[54:55], v60 offset:16384
	ds_read_b64_tr_b16 v[56:57], v61 offset:16384
	ds_read_b64_tr_b16 v[58:59], v62 offset:16384
	s_waitcnt lgkmcnt(0)
	v_mfma_f32_32x32x16_bf16 v[34:49], v[52:55], v[110:113], v[34:49]
	v_mfma_f32_32x32x16_bf16 v[18:33], v[56:59], v[110:113], v[18:33]
	ds_read_b64_tr_b16 v[52:53], v1 offset:20480
	ds_read_b64_tr_b16 v[54:55], v60 offset:20480
	ds_read_b64_tr_b16 v[56:57], v61 offset:20480
	ds_read_b64_tr_b16 v[58:59], v62 offset:20480
	s_waitcnt lgkmcnt(0)
	v_mfma_f32_32x32x16_bf16 v[34:49], v[52:55], v[106:109], v[34:49]
	v_mfma_f32_32x32x16_bf16 v[18:33], v[56:59], v[106:109], v[18:33]
	ds_read_b64_tr_b16 v[52:53], v1 offset:24576
	ds_read_b64_tr_b16 v[54:55], v60 offset:24576
	ds_read_b64_tr_b16 v[56:57], v61 offset:24576
	ds_read_b64_tr_b16 v[58:59], v62 offset:24576
	s_waitcnt lgkmcnt(0)
	v_mfma_f32_32x32x16_bf16 v[34:49], v[52:55], v[102:105], v[34:49]
	v_mfma_f32_32x32x16_bf16 v[18:33], v[56:59], v[102:105], v[18:33]
	ds_read_b64_tr_b16 v[52:53], v1 offset:28672
	ds_read_b64_tr_b16 v[54:55], v60 offset:28672
	ds_read_b64_tr_b16 v[56:57], v61 offset:28672
	ds_read_b64_tr_b16 v[58:59], v62 offset:28672
	s_waitcnt lgkmcnt(0)
	v_mfma_f32_32x32x16_bf16 v[34:49], v[52:55], v[98:101], v[34:49]
	v_mfma_f32_32x32x16_bf16 v[18:33], v[56:59], v[98:101], v[18:33]
	v_mov_b32_e32 v1, v135
	s_movk_i32 s0, 0x80
	s_nop 0
	v_permlane32_swap_b32_e32 v135, v1
	s_nop 0
	v_cmp_gt_i32_e32 vcc, s0, v134
	s_and_saveexec_b64 s[0:1], vcc
	s_xor_b64 s[4:5], exec, s[0:1]
	s_cbranch_execz .LBB0_535
	v_readlane_b32 s0, v250, 4
	s_lshl_b32 s0, s0, 4
	s_addk_i32 s0, 0x7f90
	v_add_u32_e32 v52, s0, v134
	s_movk_i32 s0, 0x6f
	v_cmp_lt_i32_e32 vcc, s0, v134
	s_nop 1
	v_cndmask_b32_e32 v52, -1, v52, vcc
